# phase 3 slot transposes: raw f32 weight loads marked nt (streamed once)
# speedup vs baseline: 1.0106x; 1.0016x over previous
.Ltrq_l2_x:
	global_load_dword v0, v[60:61], off nt
	v_lshl_add_u64 v[60:61], v[60:61], 0, s[14:15]
	global_load_dword v1, v[60:61], off nt
	v_lshl_add_u64 v[60:61], v[60:61], 0, s[14:15]
	global_load_dword v2, v[60:61], off nt
	v_lshl_add_u64 v[60:61], v[60:61], 0, s[14:15]
	global_load_dword v3, v[60:61], off nt
	v_lshl_add_u64 v[60:61], v[60:61], 0, s[14:15]
	global_load_dword v4, v[60:61], off nt
	v_lshl_add_u64 v[60:61], v[60:61], 0, s[14:15]
	global_load_dword v5, v[60:61], off nt
	v_lshl_add_u64 v[60:61], v[60:61], 0, s[14:15]
	global_load_dword v6, v[60:61], off nt
	v_lshl_add_u64 v[60:61], v[60:61], 0, s[14:15]
	global_load_dword v7, v[60:61], off nt
	v_lshl_add_u64 v[60:61], v[60:61], 0, s[14:15]
	global_load_dword v8, v[60:61], off nt
	v_lshl_add_u64 v[60:61], v[60:61], 0, s[14:15]
	global_load_dword v9, v[60:61], off nt
	v_lshl_add_u64 v[60:61], v[60:61], 0, s[14:15]
	global_load_dword v10, v[60:61], off nt
	v_lshl_add_u64 v[60:61], v[60:61], 0, s[14:15]
	global_load_dword v11, v[60:61], off nt
	v_lshl_add_u64 v[60:61], v[60:61], 0, s[14:15]
	global_load_dword v12, v[60:61], off nt
	v_lshl_add_u64 v[60:61], v[60:61], 0, s[14:15]
	global_load_dword v13, v[60:61], off nt
	v_lshl_add_u64 v[60:61], v[60:61], 0, s[14:15]
	global_load_dword v14, v[60:61], off nt
	v_lshl_add_u64 v[60:61], v[60:61], 0, s[14:15]
	global_load_dword v15, v[60:61], off nt

.Ltrq_l4_x:
	global_load_dword v16, v[62:63], off nt
	v_lshl_add_u64 v[62:63], v[62:63], 0, s[30:31]
	global_load_dword v17, v[62:63], off nt
	v_lshl_add_u64 v[62:63], v[62:63], 0, s[30:31]
	global_load_dword v18, v[62:63], off nt
	v_lshl_add_u64 v[62:63], v[62:63], 0, s[30:31]
	global_load_dword v19, v[62:63], off nt
	v_lshl_add_u64 v[62:63], v[62:63], 0, s[30:31]
	global_load_dword v20, v[62:63], off nt
	v_lshl_add_u64 v[62:63], v[62:63], 0, s[30:31]
	global_load_dword v21, v[62:63], off nt
	v_lshl_add_u64 v[62:63], v[62:63], 0, s[30:31]
	global_load_dword v22, v[62:63], off nt
	v_lshl_add_u64 v[62:63], v[62:63], 0, s[30:31]
	global_load_dword v23, v[62:63], off nt
	v_lshl_add_u64 v[62:63], v[62:63], 0, s[30:31]
	global_load_dword v24, v[62:63], off nt
	v_lshl_add_u64 v[62:63], v[62:63], 0, s[30:31]
	global_load_dword v25, v[62:63], off nt
	v_lshl_add_u64 v[62:63], v[62:63], 0, s[30:31]
	global_load_dword v26, v[62:63], off nt
	v_lshl_add_u64 v[62:63], v[62:63], 0, s[30:31]
	global_load_dword v27, v[62:63], off nt
	v_lshl_add_u64 v[62:63], v[62:63], 0, s[30:31]
	global_load_dword v28, v[62:63], off nt
	v_lshl_add_u64 v[62:63], v[62:63], 0, s[30:31]
	global_load_dword v29, v[62:63], off nt
	v_lshl_add_u64 v[62:63], v[62:63], 0, s[30:31]
	global_load_dword v30, v[62:63], off nt
	v_lshl_add_u64 v[62:63], v[62:63], 0, s[30:31]
	global_load_dword v31, v[62:63], off nt
	s_waitcnt vmcnt(16)
	s_barrier
	ds_write_b32 v38, v0 offset:0
	ds_write_b32 v38, v1 offset:1040
	ds_write_b32 v38, v2 offset:2080
	ds_write_b32 v38, v3 offset:3120
	ds_write_b32 v38, v4 offset:4160
	ds_write_b32 v38, v5 offset:5200
	ds_write_b32 v38, v6 offset:6240
	ds_write_b32 v38, v7 offset:7280
	ds_write_b32 v38, v8 offset:8320
	ds_write_b32 v38, v9 offset:9360
	ds_write_b32 v38, v10 offset:10400
	ds_write_b32 v38, v11 offset:11440
	ds_write_b32 v38, v12 offset:12480
	ds_write_b32 v38, v13 offset:13520
	ds_write_b32 v38, v14 offset:14560
	ds_write_b32 v38, v15 offset:15600
	v_lshl_add_u32 v46, v41, s20, v42
	s_waitcnt lgkmcnt(0)
	s_barrier
	ds_read2_b32 v[66:67], v40 offset0:0 offset1:32
	ds_read2_b32 v[68:69], v40 offset0:65 offset1:97
	ds_read2_b32 v[70:71], v40 offset0:130 offset1:162
	ds_read2_b32 v[72:73], v40 offset0:195 offset1:227
	ds_read2_b32 v[74:75], v44 offset0:4 offset1:36
	ds_read2_b32 v[76:77], v44 offset0:69 offset1:101
	ds_read2_b32 v[78:79], v44 offset0:134 offset1:166
	ds_read2_b32 v[80:81], v44 offset0:199 offset1:231
	v_lshl_add_u64 v[48:49], s[16:17], 0, v[46:47]
	v_lshl_add_u64 v[50:51], v[48:49], 0, s[18:19]
	s_waitcnt lgkmcnt(6)
	v_cvt_pk_bf16_f32 v52, v66, v68
	v_cvt_pk_bf16_f32 v56, v67, v69
	s_waitcnt lgkmcnt(4)
	v_cvt_pk_bf16_f32 v53, v70, v72
	v_cvt_pk_bf16_f32 v57, v71, v73
	s_waitcnt lgkmcnt(2)
	v_cvt_pk_bf16_f32 v54, v74, v76
	v_cvt_pk_bf16_f32 v58, v75, v77
	s_waitcnt lgkmcnt(0)
	v_cvt_pk_bf16_f32 v55, v78, v80
	v_cvt_pk_bf16_f32 v59, v79, v81
	global_store_dwordx4 v[48:49], v[52:55], off
	global_store_dwordx4 v[50:51], v[56:59], off
	s_addk_i32 s9, 0x100
	s_cmpk_lt_u32 s9, 0x1740
	s_cbranch_scc0 .Ltrq_last2
	s_cmpk_lt_u32 s9, 0x440
	s_cbranch_scc1 .Ltrq_p5_c0
	s_cmpk_lt_u32 s9, 0xc40
	s_cbranch_scc1 .Ltrq_p5_c1
	s_cmpk_lt_u32 s9, 0x1440
	s_cbranch_scc1 .Ltrq_p5_c2
	s_cmpk_lt_u32 s9, 0x1540
	s_cbranch_scc1 .Ltrq_p5_c3
	s_sub_u32 s7, s9, 0x1540
	s_mov_b64 s[70:71], s[80:81]
	s_mov_b64 s[12:13], s[82:83]
	s_mov_b64 s[16:17], s[86:87]
	s_mov_b32 s8, 10
	s_mov_b32 s22, 10
	s_mov_b32 s21, 1
	s_branch .Ltrq_p5_cm

.Ltrq_l6_x:
	global_load_dword v0, v[60:61], off nt
	v_lshl_add_u64 v[60:61], v[60:61], 0, s[14:15]
	global_load_dword v1, v[60:61], off nt
	v_lshl_add_u64 v[60:61], v[60:61], 0, s[14:15]
	global_load_dword v2, v[60:61], off nt
	v_lshl_add_u64 v[60:61], v[60:61], 0, s[14:15]
	global_load_dword v3, v[60:61], off nt
	v_lshl_add_u64 v[60:61], v[60:61], 0, s[14:15]
	global_load_dword v4, v[60:61], off nt
	v_lshl_add_u64 v[60:61], v[60:61], 0, s[14:15]
	global_load_dword v5, v[60:61], off nt
	v_lshl_add_u64 v[60:61], v[60:61], 0, s[14:15]
	global_load_dword v6, v[60:61], off nt
	v_lshl_add_u64 v[60:61], v[60:61], 0, s[14:15]
	global_load_dword v7, v[60:61], off nt
	v_lshl_add_u64 v[60:61], v[60:61], 0, s[14:15]
	global_load_dword v8, v[60:61], off nt
	v_lshl_add_u64 v[60:61], v[60:61], 0, s[14:15]
	global_load_dword v9, v[60:61], off nt
	v_lshl_add_u64 v[60:61], v[60:61], 0, s[14:15]
	global_load_dword v10, v[60:61], off nt
	v_lshl_add_u64 v[60:61], v[60:61], 0, s[14:15]
	global_load_dword v11, v[60:61], off nt
	v_lshl_add_u64 v[60:61], v[60:61], 0, s[14:15]
	global_load_dword v12, v[60:61], off nt
	v_lshl_add_u64 v[60:61], v[60:61], 0, s[14:15]
	global_load_dword v13, v[60:61], off nt
	v_lshl_add_u64 v[60:61], v[60:61], 0, s[14:15]
	global_load_dword v14, v[60:61], off nt
	v_lshl_add_u64 v[60:61], v[60:61], 0, s[14:15]
	global_load_dword v15, v[60:61], off nt
	s_waitcnt vmcnt(16)
	s_barrier
	ds_write_b32 v38, v16 offset:0
	ds_write_b32 v38, v17 offset:1040
	ds_write_b32 v38, v18 offset:2080
	ds_write_b32 v38, v19 offset:3120
	ds_write_b32 v38, v20 offset:4160
	ds_write_b32 v38, v21 offset:5200
	ds_write_b32 v38, v22 offset:6240
	ds_write_b32 v38, v23 offset:7280
	ds_write_b32 v38, v24 offset:8320
	ds_write_b32 v38, v25 offset:9360
	ds_write_b32 v38, v26 offset:10400
	ds_write_b32 v38, v27 offset:11440
	ds_write_b32 v38, v28 offset:12480
	ds_write_b32 v38, v29 offset:13520
	ds_write_b32 v38, v30 offset:14560
	ds_write_b32 v38, v31 offset:15600
	v_lshl_add_u32 v46, v41, s90, v42
	s_waitcnt lgkmcnt(0)
	s_barrier
	ds_read2_b32 v[66:67], v40 offset0:0 offset1:32
	ds_read2_b32 v[68:69], v40 offset0:65 offset1:97
	ds_read2_b32 v[70:71], v40 offset0:130 offset1:162
	ds_read2_b32 v[72:73], v40 offset0:195 offset1:227
	ds_read2_b32 v[74:75], v44 offset0:4 offset1:36
	ds_read2_b32 v[76:77], v44 offset0:69 offset1:101
	ds_read2_b32 v[78:79], v44 offset0:134 offset1:166
	ds_read2_b32 v[80:81], v44 offset0:199 offset1:231
	v_lshl_add_u64 v[48:49], s[34:35], 0, v[46:47]
	v_lshl_add_u64 v[50:51], v[48:49], 0, s[88:89]
	s_waitcnt lgkmcnt(6)
	v_cvt_pk_bf16_f32 v52, v66, v68
	v_cvt_pk_bf16_f32 v56, v67, v69
	s_waitcnt lgkmcnt(4)
	v_cvt_pk_bf16_f32 v53, v70, v72
	v_cvt_pk_bf16_f32 v57, v71, v73
	s_waitcnt lgkmcnt(2)
	v_cvt_pk_bf16_f32 v54, v74, v76
	v_cvt_pk_bf16_f32 v58, v75, v77
	s_waitcnt lgkmcnt(0)
	v_cvt_pk_bf16_f32 v55, v78, v80
	v_cvt_pk_bf16_f32 v59, v79, v81
	global_store_dwordx4 v[48:49], v[52:55], off
	global_store_dwordx4 v[50:51], v[56:59], off
	s_branch .Ltrq_loop
